# v047_attnq8
# baseline (speedup 1.0000x reference)
; __device__ __forceinline__ void attn_wave_item(const Params& p, int witem, const int tidx) {
;     ...
;     u32x4 vf[8], kn[8];
;     {
;       const int tn = tile > 0 ? tile - 1 : 0;
;       const char* vp = vbase + (size_t)tile * 8192;
;       const char* kp = kbase + (size_t)tn * 8192;
; #pragma unroll
;       for (int i = 0; i < 8; ++i) vf[i] = *reinterpret_cast<const u32x4*>(vp + i * 1024);
; #pragma unroll
;       for (int ks = 0; ks < 8; ++ks) kn[ks] = *reinterpret_cast<const u32x4*>(kp + ks * 1024);
;     }
;     __builtin_amdgcn_sched_barrier(0);
;     f32x16 S, S2;
; #pragma unroll
;     for (int i = 0; i < 16; ++i) { S[i] = 0.f; S2[i] = 0.f; }
; #pragma unroll
;     for (int ks = 0; ks < 8; ks += 2) {
;       u32x4 qa = *reinterpret_cast<const u32x4*>(qlds + ks * 1024);
;       u32x4 qb = *reinterpret_cast<const u32x4*>(qlds + (ks + 1) * 1024);
;       S = __builtin_amdgcn_mfma_f32_32x32x16_bf16(as_bf16x8(kf[ks]), as_bf16x8(qa), S, 0, 0, 0);
;       S2 = __builtin_amdgcn_mfma_f32_32x32x16_bf16(as_bf16x8(kf[ks + 1]), as_bf16x8(qb), S2, 0, 0, 0);
;     }
; #pragma unroll
;     for (int i = 0; i < 16; ++i) S[i] += S2[i];
.LBB0_119:
	ds_read_b128 v[226:229], v173
	ds_read_b128 v[84:87], v173 offset:1024
	ds_read_b128 v[204:207], v173 offset:2048
	ds_read_b128 v[222:225], v173 offset:3072
	ds_read_b128 v[230:233], v173 offset:4096
	ds_read_b128 v[234:237], v173 offset:5120
	ds_read_b128 v[238:241], v173 offset:6144
	ds_read_b128 v[242:245], v173 offset:7168
	v_lshl_add_u64 v[68:69], v[174:175], 0, s[48:49]
	s_mov_b32 s42, 0x20900000
	v_add_co_u32_e64 v72, s[42:43], s42, v68
	v_sub_u32_e64 v162, v169, 1 clamp
	s_nop 0
	v_addc_co_u32_e64 v73, s[42:43], 0, v69, s[42:43]
	s_mov_b32 s42, 0x20901000
	s_nop 0
	v_add_co_u32_e64 v68, s[42:43], s42, v68
	v_lshlrev_b64 v[70:71], 13, v[162:163]
	s_nop 0
	v_addc_co_u32_e64 v69, s[42:43], 0, v69, s[42:43]
	global_load_dwordx4 v[154:157], v[72:73], off offset:1024
	global_load_dwordx4 v[150:153], v[72:73], off offset:2048
	global_load_dwordx4 v[142:145], v[72:73], off offset:3072
	global_load_dwordx4 v[158:161], v[68:69], off offset:-4096
	global_load_dwordx4 v[146:149], v[68:69], off
	global_load_dwordx4 v[138:141], v[68:69], off offset:1024
	global_load_dwordx4 v[134:137], v[68:69], off offset:2048
	global_load_dwordx4 v[130:133], v[68:69], off offset:3072
	s_waitcnt vmcnt(12)
	v_mov_b64_e32 v[198:199], v[112:113]
	v_mov_b64_e32 v[202:203], v[108:109]
	v_mov_b64_e32 v[80:81], v[102:103]
	v_mov_b64_e32 v[64:65], v[98:99]
	v_lshl_add_u64 v[68:69], v[170:171], 0, v[70:71]
	v_mov_b64_e32 v[196:197], v[110:111]
	v_mov_b64_e32 v[200:201], v[106:107]
	v_mov_b64_e32 v[82:83], v[104:105]
	v_mov_b64_e32 v[66:67], v[100:101]
	global_load_dwordx4 v[98:101], v[68:69], off
	global_load_dwordx4 v[102:105], v[68:69], off offset:1024
	global_load_dwordx4 v[106:109], v[68:69], off offset:2048
	global_load_dwordx4 v[110:113], v[68:69], off offset:3072
	v_add_co_u32_e64 v68, s[42:43], s58, v68
	s_waitcnt vmcnt(12)
	v_mov_b64_e32 v[182:183], v[128:129]
	v_mov_b64_e32 v[186:187], v[124:125]
	v_mov_b64_e32 v[190:191], v[120:121]
	v_mov_b64_e32 v[194:195], v[116:117]
	v_addc_co_u32_e64 v69, s[42:43], 0, v69, s[42:43]
	v_mov_b64_e32 v[180:181], v[126:127]
	v_mov_b64_e32 v[184:185], v[122:123]
	v_mov_b64_e32 v[188:189], v[118:119]
	v_mov_b64_e32 v[192:193], v[114:115]
	global_load_dwordx4 v[114:117], v[68:69], off
	global_load_dwordx4 v[118:121], v[68:69], off offset:1024
	global_load_dwordx4 v[122:125], v[68:69], off offset:2048
	global_load_dwordx4 v[126:129], v[68:69], off offset:3072
	s_cmp_lg_u32 s48, 0
	s_cselect_b64 s[50:51], -1, 0
	s_waitcnt lgkmcnt(7)
	s_setprio 1
	v_mfma_f32_32x32x16_bf16 v[64:79], v[64:67], v[226:229], 0
	s_or_b64 s[44:45], s[6:7], s[50:51]
	s_waitcnt lgkmcnt(6)
	v_mfma_f32_32x32x16_bf16 v[80:95], v[80:83], v[84:87], 0
	s_waitcnt lgkmcnt(5)
	v_mfma_f32_32x32x16_bf16 v[64:79], v[200:203], v[204:207], v[64:79]
	s_waitcnt lgkmcnt(4)
	v_mfma_f32_32x32x16_bf16 v[80:95], v[196:199], v[222:225], v[80:95]
	s_waitcnt lgkmcnt(3)
	v_mfma_f32_32x32x16_bf16 v[64:79], v[192:195], v[230:233], v[64:79]
	s_waitcnt lgkmcnt(2)
	v_mfma_f32_32x32x16_bf16 v[80:95], v[188:191], v[234:237], v[80:95]
	s_waitcnt lgkmcnt(1)
	v_mfma_f32_32x32x16_bf16 v[64:79], v[184:187], v[238:241], v[64:79]
	s_waitcnt lgkmcnt(0)
	v_mfma_f32_32x32x16_bf16 v[80:95], v[180:183], v[242:245], v[80:95]
	s_setprio 0
	s_nop 11
	v_add_f32_e32 v64, v64, v80
	v_exp_f32_e64 v80, -|v64|
	v_add_f32_e32 v65, v65, v81
	v_add_f32_e32 v66, v66, v82
	v_exp_f32_e64 v82, -|v65|
	v_add_f32_e32 v81, 1.0, v80
	v_rcp_f32_e32 v81, v81
	v_add_f32_e32 v67, v67, v83
	v_add_f32_e32 v83, 1.0, v82
	v_cmp_le_f32_e64 s[42:43], 0, v64
	v_mul_f32_e32 v80, v80, v81
	v_rcp_f32_e32 v83, v83
	v_cndmask_b32_e64 v64, v80, v81, s[42:43]
	v_add_f32_e32 v68, v68, v84
	v_cndmask_b32_e64 v84, 0, v64, s[44:45]
	v_cndmask_b32_e64 v64, v81, v80, s[42:43]
	v_exp_f32_e64 v81, -|v66|
	v_cndmask_b32_e64 v80, 1.0, v64, s[44:45]
	v_mul_f32_e32 v64, v82, v83
	v_cmp_le_f32_e64 s[42:43], 0, v65
	s_or_b64 s[44:45], s[8:9], s[50:51]
	v_add_f32_e32 v69, v69, v85
	v_cndmask_b32_e64 v65, v64, v83, s[42:43]
	v_cndmask_b32_e64 v64, v83, v64, s[42:43]
	v_cndmask_b32_e64 v82, 0, v65, s[44:45]
	v_add_f32_e32 v65, 1.0, v81
	v_cndmask_b32_e64 v83, 1.0, v64, s[44:45]
	v_exp_f32_e64 v64, -|v67|
	v_rcp_f32_e32 v65, v65
	v_cmp_le_f32_e64 s[42:43], 0, v66
	s_or_b64 s[44:45], s[10:11], s[50:51]
	v_add_f32_e32 v85, 1.0, v64
	v_mul_f32_e32 v81, v81, v65
	v_rcp_f32_e32 v85, v85
	v_cndmask_b32_e64 v66, v81, v65, s[42:43]
	v_cndmask_b32_e64 v65, v65, v81, s[42:43]
	v_cndmask_b32_e64 v81, 1.0, v65, s[44:45]
	v_exp_f32_e64 v65, -|v68|
	v_mul_f32_e32 v64, v64, v85
	v_cmp_le_f32_e64 s[42:43], 0, v67
	v_exp_f32_e64 v67, -|v69|
	v_add_f32_e32 v70, v70, v86
	v_cndmask_b32_e64 v86, 0, v66, s[44:45]
	v_cndmask_b32_e64 v66, v64, v85, s[42:43]
	s_or_b64 s[44:45], s[12:13], s[50:51]
	v_add_f32_e32 v71, v71, v87
	v_cndmask_b32_e64 v87, 0, v66, s[44:45]
	v_add_f32_e32 v66, 1.0, v65
	v_rcp_f32_e32 v66, v66
	v_cndmask_b32_e64 v64, v85, v64, s[42:43]
	v_cmp_le_f32_e64 s[42:43], 0, v68
	v_add_f32_e32 v68, 1.0, v67
	v_rcp_f32_e32 v68, v68
	v_cndmask_b32_e64 v85, 1.0, v64, s[44:45]
	v_mul_f32_e32 v64, v65, v66
	v_cndmask_b32_e64 v65, v64, v66, s[42:43]
	s_or_b64 s[44:45], s[14:15], s[50:51]
	v_add_f32_e32 v72, v72, v88
	v_cndmask_b32_e64 v88, 0, v65, s[44:45]
	v_mul_f32_e32 v65, v67, v68
	v_exp_f32_e64 v67, -|v70|
	v_cndmask_b32_e64 v64, v66, v64, s[42:43]
	v_cmp_le_f32_e64 s[42:43], 0, v69
	v_cndmask_b32_e64 v64, 1.0, v64, s[44:45]
	s_or_b64 s[44:45], s[16:17], s[50:51]
	v_cndmask_b32_e64 v66, v65, v68, s[42:43]
	v_add_f32_e32 v73, v73, v89
	v_cndmask_b32_e64 v89, 0, v66, s[44:45]
	v_add_f32_e32 v66, 1.0, v67
	v_cndmask_b32_e64 v65, v68, v65, s[42:43]
; __device__ __forceinline__ void attn_wave_item(const Params& p, int witem, const int tidx) {
;     ...
;     for (int r = 0; r < 16; ++r) {
;       float z = S[r];
;       float e = __builtin_amdgcn_exp2f(-fabsf(z));
;       float rr = __builtin_amdgcn_rcpf(1.f + e);
;       float sm = e * rr;
;       int kl = (r & 3) + 8 * (r >> 2) + 4 * half;
;       bool v = !diag || (kl < n);
;       bool pos = z >= 0.f;
;       be[r] = v ? (pos ? rr : sm) : 0.f;
;       om[r] = v ? (pos ? sm : rr) : 1.f;
;     }
;     float gp[4], pgp[4];
; #pragma unroll
;     for (int gi = 0; gi < 4; ++gi) {
;       gp[gi] = (om[4 * gi] * om[4 * gi + 1]) * (om[4 * gi + 2] * om[4 * gi + 3]);
;       pgp[gi] = __shfl_xor(gp[gi], 32, 64);
;     }
;     float w[16];
;     float run = R;
; #pragma unroll
;     ...
;       float a = (half == 0) ? (run * pgp[gi]) : run;
; #pragma unroll
;       for (int r = 3; r >= 0; --r) {
;         int ri = 4 * gi + r;
;         w[ri] = be[ri] * a;
;         a *= om[ri];
;       }
;       run *= gp[gi] * pgp[gi];
;     }
;     R = run;
;     __builtin_amdgcn_sched_barrier(0);
;     bf16x8 pf[2];
; #pragma unroll
;     for (int m = 0; m < 2; ++m) {
;       u32x4 t;
;       t.x = pack2(w[8 * m + 0], w[8 * m + 1]);
;       t.y = pack2(w[8 * m + 2], w[8 * m + 3]);
;       t.z = pack2(w[8 * m + 4], w[8 * m + 5]);
;       t.w = pack2(w[8 * m + 6], w[8 * m + 7]);
;       pf[m] = as_bf16x8(t);
;     }
; #pragma unroll
;     for (int dt = 0; dt < 4; ++dt)
; #pragma unroll
;       for (int m = 0; m < 2; ++m) O[dt] = __builtin_amdgcn_mfma_f32_32x32x16_bf16(as_bf16x8(vf[dt * 2 + m]), pf[m], O[dt], 0, 0, 0);
;     if (__all(R < 1.17549435e-38f)) break;
;     __builtin_amdgcn_sched_barrier(0);
; #pragma unroll
;     for (int i = 0; i < 8; ++i) kf[i] = kn[i];
;   }
	v_rcp_f32_e32 v69, v66
	v_cndmask_b32_e64 v66, 1.0, v65, s[44:45]
	v_exp_f32_e64 v65, -|v71|
	v_cmp_le_f32_e64 s[42:43], 0, v70
	v_mul_f32_e32 v67, v67, v69
	s_or_b64 s[44:45], s[18:19], s[50:51]
	v_add_f32_e32 v70, 1.0, v65
	v_rcp_f32_e32 v70, v70
	v_cndmask_b32_e64 v68, v67, v69, s[42:43]
	v_cndmask_b32_e64 v67, v69, v67, s[42:43]
	v_cndmask_b32_e64 v176, 1.0, v67, s[44:45]
	v_exp_f32_e64 v67, -|v72|
	v_mul_f32_e32 v65, v65, v70
	v_cmp_le_f32_e64 s[42:43], 0, v71
	v_add_f32_e32 v74, v74, v90
	v_cndmask_b32_e64 v90, 0, v68, s[44:45]
	v_cndmask_b32_e64 v68, v65, v70, s[42:43]
	s_or_b64 s[44:45], s[20:21], s[50:51]
	v_cndmask_b32_e64 v71, 0, v68, s[44:45]
	v_add_f32_e32 v68, 1.0, v67
	v_cndmask_b32_e64 v65, v70, v65, s[42:43]
	v_rcp_f32_e32 v69, v68
	v_cndmask_b32_e64 v68, 1.0, v65, s[44:45]
	v_exp_f32_e64 v65, -|v73|
	v_cmp_le_f32_e64 s[42:43], 0, v72
	v_mul_f32_e32 v67, v67, v69
	s_or_b64 s[44:45], s[22:23], s[50:51]
	v_add_f32_e32 v72, 1.0, v65
	v_rcp_f32_e32 v72, v72
	v_cndmask_b32_e64 v70, v67, v69, s[42:43]
	v_cndmask_b32_e64 v67, v69, v67, s[42:43]
	v_cmp_le_f32_e64 s[42:43], 0, v73
	v_mul_f32_e32 v65, v65, v72
	v_add_f32_e32 v75, v75, v91
	v_cndmask_b32_e64 v91, 0, v70, s[44:45]
	v_cndmask_b32_e64 v67, 1.0, v67, s[44:45]
	v_exp_f32_e64 v69, -|v74|
	v_cndmask_b32_e64 v70, v65, v72, s[42:43]
	s_or_b64 s[44:45], s[24:25], s[50:51]
	v_cndmask_b32_e64 v65, v72, v65, s[42:43]
	v_add_f32_e32 v77, v77, v93
	v_cndmask_b32_e64 v93, 1.0, v65, s[44:45]
	v_exp_f32_e64 v65, -|v75|
	v_add_f32_e32 v76, v76, v92
	v_cndmask_b32_e64 v92, 0, v70, s[44:45]
	v_add_f32_e32 v70, 1.0, v69
	v_rcp_f32_e32 v70, v70
	v_add_f32_e32 v73, 1.0, v65
	v_rcp_f32_e32 v73, v73
	v_cmp_le_f32_e64 s[42:43], 0, v74
	v_mul_f32_e32 v69, v69, v70
	s_or_b64 s[44:45], s[26:27], s[50:51]
	v_cndmask_b32_e64 v72, v69, v70, s[42:43]
	v_cndmask_b32_e64 v69, v70, v69, s[42:43]
	v_mul_f32_e32 v65, v65, v73
	v_cmp_le_f32_e64 s[42:43], 0, v75
	v_add_f32_e32 v78, v78, v94
	v_add_f32_e32 v79, v79, v95
	v_cndmask_b32_e64 v94, 0, v72, s[44:45]
	v_cndmask_b32_e64 v95, 1.0, v69, s[44:45]
	v_exp_f32_e64 v69, -|v76|
	v_cndmask_b32_e64 v70, v65, v73, s[42:43]
	s_or_b64 s[44:45], s[28:29], s[50:51]
	v_cndmask_b32_e64 v65, v73, v65, s[42:43]
	v_cndmask_b32_e64 v179, 1.0, v65, s[44:45]
	v_exp_f32_e64 v65, -|v77|
	v_cndmask_b32_e64 v162, 0, v70, s[44:45]
	v_add_f32_e32 v70, 1.0, v69
	v_rcp_f32_e32 v70, v70
	v_add_f32_e32 v73, 1.0, v65
	v_rcp_f32_e32 v73, v73
	v_cmp_le_f32_e64 s[42:43], 0, v76
	v_mul_f32_e32 v69, v69, v70
	s_or_b64 s[44:45], s[30:31], s[50:51]
	v_cndmask_b32_e64 v72, v69, v70, s[42:43]
	v_cndmask_b32_e64 v69, v70, v69, s[42:43]
	v_mul_f32_e32 v65, v65, v73
	v_cmp_le_f32_e64 s[42:43], 0, v77
	v_cndmask_b32_e64 v74, 0, v72, s[44:45]
	v_cndmask_b32_e64 v69, 1.0, v69, s[44:45]
	v_exp_f32_e64 v70, -|v78|
	v_cndmask_b32_e64 v72, v65, v73, s[42:43]
	s_or_b64 s[44:45], s[34:35], s[50:51]
	v_cndmask_b32_e64 v65, v73, v65, s[42:43]
	v_cndmask_b32_e64 v73, 1.0, v65, s[44:45]
	v_exp_f32_e64 v65, -|v79|
	v_cndmask_b32_e64 v75, 0, v72, s[44:45]
	v_add_f32_e32 v72, 1.0, v70
	v_rcp_f32_e32 v72, v72
	v_add_f32_e32 v77, 1.0, v65
	v_rcp_f32_e32 v77, v77
	v_cmp_le_f32_e64 s[42:43], 0, v78
	v_mul_f32_e32 v70, v70, v72
	s_or_b64 s[44:45], s[36:37], s[50:51]
	v_cndmask_b32_e64 v76, v70, v72, s[42:43]
	v_cndmask_b32_e64 v70, v72, v70, s[42:43]
	v_mul_f32_e32 v65, v65, v77
	v_cmp_le_f32_e64 s[42:43], 0, v79
	v_cndmask_b32_e64 v76, 0, v76, s[44:45]
	v_cndmask_b32_e64 v78, 1.0, v70, s[44:45]
	v_cndmask_b32_e64 v70, v65, v77, s[42:43]
	s_or_b64 s[44:45], s[38:39], s[50:51]
	v_cndmask_b32_e64 v65, v77, v65, s[42:43]
	v_cndmask_b32_e64 v77, 1.0, v65, s[44:45]
	v_mul_f32_e32 v65, v69, v73
	v_mul_f32_e32 v69, v78, v77
	v_mul_f32_e32 v69, v65, v69
	v_cndmask_b32_e64 v79, 0, v70, s[44:45]
	v_mul_f32_e32 v70, v80, v83
	ds_bpermute_b32 v80, v178, v69
	v_mul_f32_e32 v65, v67, v93
	v_mul_f32_e32 v67, v95, v179
	v_mul_f32_e32 v65, v65, v67
	ds_bpermute_b32 v67, v178, v65
	s_waitcnt lgkmcnt(1)
	v_mul_f32_e32 v180, v177, v80
	v_cndmask_b32_e32 v180, v177, v180, vcc
	v_mul_f32_e32 v77, v180, v77
	v_mul_f32_e32 v76, v76, v77
	v_mul_f32_e32 v77, v78, v77
	v_mul_f32_e32 v73, v73, v77
	v_mul_f32_e32 v69, v69, v80
	v_mul_f32_e32 v78, v75, v77
	v_mul_f32_e32 v77, v74, v73
	v_pk_mul_f32 v[74:75], v[176:177], v[68:69]
	s_waitcnt lgkmcnt(0)
	v_pk_mul_f32 v[64:65], v[64:65], v[66:67]
	v_mul_f32_e32 v67, v75, v67
	v_pk_mul_f32 v[64:65], v[64:65], v[74:75]
	ds_bpermute_b32 v73, v178, v64
	v_cndmask_b32_e32 v67, v75, v67, vcc
	v_mul_f32_e32 v74, v162, v67
	v_mul_f32_e32 v67, v179, v67
	v_mul_f32_e32 v75, v94, v67
	v_mul_f32_e32 v67, v95, v67
	v_mul_f32_e32 v80, v92, v67
	v_mul_f32_e32 v67, v93, v67
	v_mul_f32_e32 v91, v91, v67
	s_waitcnt lgkmcnt(0)
	v_mul_f32_e32 v67, v65, v73
	v_cndmask_b32_e32 v67, v65, v67, vcc
	v_mul_f32_e32 v72, v81, v85
	v_mul_f32_e32 v92, v71, v67
	v_mov_b32_e32 v71, v64
	v_mul_f32_e32 v67, v68, v67
	v_pk_mul_f32 v[68:69], v[70:71], v[72:73]
	ds_bpermute_b32 v64, v178, v68
	v_mul_f32_e32 v90, v90, v67
	v_mul_f32_e32 v67, v176, v67
	v_mul_f32_e32 v70, v89, v67
	v_mul_f32_e32 v66, v66, v67
	s_waitcnt lgkmcnt(0)
	v_pk_mul_f32 v[72:73], v[68:69], v[64:65]
	v_mul_f32_e32 v79, v180, v79
	v_mul_f32_e32 v64, v73, v64
	v_cndmask_b32_e32 v64, v73, v64, vcc
	v_mul_f32_e32 v65, v87, v64
	v_mul_f32_e32 v64, v85, v64
	v_mul_f32_e32 v67, v86, v64
	v_mul_f32_e32 v64, v81, v64
	v_mul_f32_e32 v68, v82, v64
	v_mul_f32_e32 v64, v83, v64
	v_mul_f32_e32 v66, v88, v66
	v_mul_f32_e32 v64, v84, v64
	v_cvt_pk_bf16_f32 v64, v64, v68
	v_cvt_pk_bf16_f32 v65, v67, v65
	v_cvt_pk_bf16_f32 v66, v66, v70
	v_cvt_pk_bf16_f32 v67, v90, v92
	v_cvt_pk_bf16_f32 v68, v91, v80
	v_cvt_pk_bf16_f32 v69, v75, v74
	v_cvt_pk_bf16_f32 v70, v77, v78
	v_cvt_pk_bf16_f32 v71, v76, v79
	v_mul_f32_e32 v177, v72, v73
	s_waitcnt vmcnt(12)
	s_setprio 1
	v_mfma_f32_32x32x16_bf16 v[48:63], v[158:161], v[64:67], v[48:63]
	v_cmp_gt_f32_e64 s[42:43], s1, v177
	s_or_b64 s[92:93], s[92:93], exec
	s_mov_b64 s[44:45], -1
	s_cmp_lg_u64 s[42:43], exec
	v_mfma_f32_32x32x16_bf16 v[32:47], v[150:153], v[64:67], v[32:47]
	s_waitcnt vmcnt(11)
	v_mfma_f32_32x32x16_bf16 v[16:31], v[146:149], v[64:67], v[16:31]
	s_waitcnt vmcnt(9)
	v_mfma_f32_32x32x16_bf16 v[0:15], v[134:137], v[64:67], v[0:15]
	v_mfma_f32_32x32x16_bf16 v[48:63], v[154:157], v[68:71], v[48:63]
	v_mfma_f32_32x32x16_bf16 v[32:47], v[142:145], v[68:71], v[32:47]
	v_mfma_f32_32x32x16_bf16 v[16:31], v[138:141], v[68:71], v[16:31]
	s_waitcnt vmcnt(8)
	v_mfma_f32_32x32x16_bf16 v[0:15], v[130:133], v[68:71], v[0:15]
	s_setprio 0
	s_cbranch_scc1 .LBB0_117
	s_branch .LBB0_118
